# ffup epilogue as a 2-iteration loop over the row blocks (half the code size; second pass after moving the mi=1 accumulators down)
# baseline (speedup 1.0000x reference)
.LBB0_1034:
	v_lshl_or_b32 v115, v183, 3, v191
	v_lshrrev_b32_e32 v116, 6, v115
	v_and_b32_e32 v117, 63, v115
	v_lshlrev_b32_e32 v113, 11, v116
	v_add_u32_e32 v113, 0x10000, v113
	v_readfirstlane_b32 s100, v116
	v_and_b32_e32 v112, 31, v117
	v_lshl_add_u32 v112, v112, 1, v113
	v_lshrrev_b32_e32 v116, 5, v117
	v_lshl_add_u32 v112, v116, 8, v112
	v_lshl_add_u32 v113, v117, 4, v113
	v_lshrrev_b32_e32 v116, 2, v117
	v_mul_u32_u24_e32 v116, 0x1600, v116
	v_and_b32_e32 v114, 3, v117
	v_lshl_add_u32 v114, v114, 4, v116
	s_lshr_b32 s101, s100, 1
	s_lshl_b32 s101, s101, 6
	s_add_u32 s101, s101, s48
	s_mul_i32 s101, s101, 0x1600
	s_and_b32 s100, s100, 1
	s_lshl_b32 s100, s100, 6
	s_add_u32 s100, s100, s49
	s_add_u32 s101, s101, s100
	s_add_u32 s98, s90, 0x3971900
	s_addc_u32 s99, s91, 0
	s_add_u32 s98, s98, s101
	s_addc_u32 s99, s99, 0
	s_mov_b32 s101, 0
.Lffl2_iter:
	v_mul_f32_e32 v64, 0xbfb8aa3b, v48
	v_mul_f32_e32 v70, 0xbfb8aa3b, v49
	v_mul_f32_e32 v76, 0xbfb8aa3b, v50
	v_mul_f32_e32 v82, 0xbfb8aa3b, v51
	v_exp_f32_e32 v64, v64
	v_exp_f32_e32 v70, v70
	v_exp_f32_e32 v76, v76
	v_exp_f32_e32 v82, v82
	v_add_f32_e32 v64, 1.0, v64
	v_add_f32_e32 v70, 1.0, v70
	v_add_f32_e32 v76, 1.0, v76
	v_add_f32_e32 v82, 1.0, v82
	v_div_scale_f32 v65, s[2:3], v64, v64, 1.0
	v_div_scale_f32 v71, s[2:3], v70, v70, 1.0
	v_div_scale_f32 v77, s[2:3], v76, v76, 1.0
	v_div_scale_f32 v83, s[2:3], v82, v82, 1.0
	v_rcp_f32_e32 v66, v65
	v_rcp_f32_e32 v72, v71
	v_rcp_f32_e32 v78, v77
	v_rcp_f32_e32 v84, v83
	v_fma_f32 v69, -v65, v66, 1.0
	v_fma_f32 v75, -v71, v72, 1.0
	v_fma_f32 v81, -v77, v78, 1.0
	v_fma_f32 v87, -v83, v84, 1.0
	v_fmac_f32_e32 v66, v69, v66
	v_fmac_f32_e32 v72, v75, v72
	v_fmac_f32_e32 v78, v81, v78
	v_fmac_f32_e32 v84, v87, v84
	v_div_scale_f32 v67, vcc, 1.0, v64, 1.0
	v_mul_f32_e32 v88, 0xbfb8aa3b, v52
	v_mul_f32_e32 v68, v67, v66
	v_mul_f32_e32 v94, 0xbfb8aa3b, v53
	v_fma_f32 v69, -v65, v68, v67
	v_mul_f32_e32 v100, 0xbfb8aa3b, v54
	v_fmac_f32_e32 v68, v69, v66
	v_mul_f32_e32 v106, 0xbfb8aa3b, v55
	v_fma_f32 v65, -v65, v68, v67
	v_exp_f32_e32 v88, v88
	v_div_fmas_f32 v65, v65, v66, v68
	v_exp_f32_e32 v94, v94
	v_div_scale_f32 v73, vcc, 1.0, v70, 1.0
	v_exp_f32_e32 v100, v100
	v_mul_f32_e32 v74, v73, v72
	v_exp_f32_e32 v106, v106
	v_fma_f32 v75, -v71, v74, v73
	v_add_f32_e32 v88, 1.0, v88
	v_fmac_f32_e32 v74, v75, v72
	v_add_f32_e32 v94, 1.0, v94
	v_fma_f32 v71, -v71, v74, v73
	v_add_f32_e32 v100, 1.0, v100
	v_div_fmas_f32 v71, v71, v72, v74
	v_add_f32_e32 v106, 1.0, v106
	v_div_scale_f32 v79, vcc, 1.0, v76, 1.0
	v_div_scale_f32 v89, s[2:3], v88, v88, 1.0
	v_mul_f32_e32 v80, v79, v78
	v_div_scale_f32 v95, s[2:3], v94, v94, 1.0
	v_fma_f32 v81, -v77, v80, v79
	v_div_scale_f32 v101, s[2:3], v100, v100, 1.0
	v_fmac_f32_e32 v80, v81, v78
	v_div_scale_f32 v107, s[2:3], v106, v106, 1.0
	v_fma_f32 v77, -v77, v80, v79
	v_rcp_f32_e32 v90, v89
	v_div_fmas_f32 v77, v77, v78, v80
	v_rcp_f32_e32 v96, v95
	v_div_scale_f32 v85, vcc, 1.0, v82, 1.0
	v_rcp_f32_e32 v102, v101
	v_mul_f32_e32 v86, v85, v84
	v_rcp_f32_e32 v108, v107
	v_fma_f32 v87, -v83, v86, v85
	v_fma_f32 v93, -v89, v90, 1.0
	v_fmac_f32_e32 v86, v87, v84
	v_fma_f32 v99, -v95, v96, 1.0
	v_fma_f32 v83, -v83, v86, v85
	v_fma_f32 v105, -v101, v102, 1.0
	v_div_fmas_f32 v83, v83, v84, v86
	v_fma_f32 v111, -v107, v108, 1.0
	v_fmac_f32_e32 v90, v93, v90
	v_fmac_f32_e32 v96, v99, v96
	v_fmac_f32_e32 v102, v105, v102
	v_fmac_f32_e32 v108, v111, v108
	v_div_fixup_f32 v65, v65, v64, 1.0
	v_div_fixup_f32 v71, v71, v70, 1.0
	v_div_fixup_f32 v77, v77, v76, 1.0
	v_div_fixup_f32 v83, v83, v82, 1.0
	v_mul_f32_e32 v65, v48, v65
	v_mul_f32_e32 v71, v49, v71
	v_mul_f32_e32 v77, v50, v77
	v_mul_f32_e32 v83, v51, v83
	v_mul_f32_e32 v65, v32, v65
	v_mul_f32_e32 v71, v33, v71
	v_mul_f32_e32 v77, v34, v77
	v_mul_f32_e32 v83, v35, v83
	v_cvt_pk_bf16_f32 v65, v65, v65
	v_cvt_pk_bf16_f32 v71, v71, v71
	v_cvt_pk_bf16_f32 v77, v77, v77
	v_cvt_pk_bf16_f32 v83, v83, v83
	ds_write_b16 v112, v65
	ds_write_b16 v112, v71 offset:64
	ds_write_b16 v112, v77 offset:128
	ds_write_b16 v112, v83 offset:192
	v_div_scale_f32 v91, vcc, 1.0, v88, 1.0
	v_mul_f32_e32 v64, 0xbfb8aa3b, v56
	v_mul_f32_e32 v92, v91, v90
	v_mul_f32_e32 v70, 0xbfb8aa3b, v57
	v_fma_f32 v93, -v89, v92, v91
	v_mul_f32_e32 v76, 0xbfb8aa3b, v58
	v_fmac_f32_e32 v92, v93, v90
	v_mul_f32_e32 v82, 0xbfb8aa3b, v59
	v_fma_f32 v89, -v89, v92, v91
	v_exp_f32_e32 v64, v64
	v_div_fmas_f32 v89, v89, v90, v92
	v_exp_f32_e32 v70, v70
	v_div_scale_f32 v97, vcc, 1.0, v94, 1.0
	v_exp_f32_e32 v76, v76
	v_mul_f32_e32 v98, v97, v96
	v_exp_f32_e32 v82, v82
	v_fma_f32 v99, -v95, v98, v97
	v_add_f32_e32 v64, 1.0, v64
	v_fmac_f32_e32 v98, v99, v96
	v_add_f32_e32 v70, 1.0, v70
	v_fma_f32 v95, -v95, v98, v97
	v_add_f32_e32 v76, 1.0, v76
	v_div_fmas_f32 v95, v95, v96, v98
	v_add_f32_e32 v82, 1.0, v82
	v_div_scale_f32 v103, vcc, 1.0, v100, 1.0
	v_div_scale_f32 v65, s[2:3], v64, v64, 1.0
	v_mul_f32_e32 v104, v103, v102
	v_div_scale_f32 v71, s[2:3], v70, v70, 1.0
	v_fma_f32 v105, -v101, v104, v103
	v_div_scale_f32 v77, s[2:3], v76, v76, 1.0
	v_fmac_f32_e32 v104, v105, v102
	v_div_scale_f32 v83, s[2:3], v82, v82, 1.0
	v_fma_f32 v101, -v101, v104, v103
	v_rcp_f32_e32 v66, v65
	v_div_fmas_f32 v101, v101, v102, v104
	v_rcp_f32_e32 v72, v71
	v_div_scale_f32 v109, vcc, 1.0, v106, 1.0
	v_rcp_f32_e32 v78, v77
	v_mul_f32_e32 v110, v109, v108
	v_rcp_f32_e32 v84, v83
	v_fma_f32 v111, -v107, v110, v109
	v_fma_f32 v69, -v65, v66, 1.0
	v_fmac_f32_e32 v110, v111, v108
	v_fma_f32 v75, -v71, v72, 1.0
	v_fma_f32 v107, -v107, v110, v109
	v_fma_f32 v81, -v77, v78, 1.0
	v_div_fmas_f32 v107, v107, v108, v110
	v_fma_f32 v87, -v83, v84, 1.0
	v_fmac_f32_e32 v66, v69, v66
	v_fmac_f32_e32 v72, v75, v72
	v_fmac_f32_e32 v78, v81, v78
	v_fmac_f32_e32 v84, v87, v84
	v_div_fixup_f32 v89, v89, v88, 1.0
	v_div_fixup_f32 v95, v95, v94, 1.0
	v_div_fixup_f32 v101, v101, v100, 1.0
	v_div_fixup_f32 v107, v107, v106, 1.0
	v_mul_f32_e32 v89, v52, v89
	v_mul_f32_e32 v95, v53, v95
	v_mul_f32_e32 v101, v54, v101
	v_mul_f32_e32 v107, v55, v107
	v_mul_f32_e32 v89, v36, v89
	v_mul_f32_e32 v95, v37, v95
	v_mul_f32_e32 v101, v38, v101
	v_mul_f32_e32 v107, v39, v107
	v_cvt_pk_bf16_f32 v89, v89, v89
	v_cvt_pk_bf16_f32 v95, v95, v95
	v_cvt_pk_bf16_f32 v101, v101, v101
	v_cvt_pk_bf16_f32 v107, v107, v107
	ds_write_b16 v112, v89 offset:512
	ds_write_b16 v112, v95 offset:576
	ds_write_b16 v112, v101 offset:640
	ds_write_b16 v112, v107 offset:704
	v_div_scale_f32 v67, vcc, 1.0, v64, 1.0
	v_mul_f32_e32 v88, 0xbfb8aa3b, v60
	v_mul_f32_e32 v68, v67, v66
	v_mul_f32_e32 v94, 0xbfb8aa3b, v61
	v_fma_f32 v69, -v65, v68, v67
	v_mul_f32_e32 v100, 0xbfb8aa3b, v62
	v_fmac_f32_e32 v68, v69, v66
	v_mul_f32_e32 v106, 0xbfb8aa3b, v63
	v_fma_f32 v65, -v65, v68, v67
	v_exp_f32_e32 v88, v88
	v_div_fmas_f32 v65, v65, v66, v68
	v_exp_f32_e32 v94, v94
	v_div_scale_f32 v73, vcc, 1.0, v70, 1.0
	v_exp_f32_e32 v100, v100
	v_mul_f32_e32 v74, v73, v72
	v_exp_f32_e32 v106, v106
	v_fma_f32 v75, -v71, v74, v73
	v_add_f32_e32 v88, 1.0, v88
	v_fmac_f32_e32 v74, v75, v72
	v_add_f32_e32 v94, 1.0, v94
	v_fma_f32 v71, -v71, v74, v73
	v_add_f32_e32 v100, 1.0, v100
	v_div_fmas_f32 v71, v71, v72, v74
	v_add_f32_e32 v106, 1.0, v106
	v_div_scale_f32 v79, vcc, 1.0, v76, 1.0
	v_div_scale_f32 v89, s[2:3], v88, v88, 1.0
	v_mul_f32_e32 v80, v79, v78
	v_div_scale_f32 v95, s[2:3], v94, v94, 1.0
	v_fma_f32 v81, -v77, v80, v79
	v_div_scale_f32 v101, s[2:3], v100, v100, 1.0
	v_fmac_f32_e32 v80, v81, v78
	v_div_scale_f32 v107, s[2:3], v106, v106, 1.0
	v_fma_f32 v77, -v77, v80, v79
	v_rcp_f32_e32 v90, v89
	v_div_fmas_f32 v77, v77, v78, v80
	v_rcp_f32_e32 v96, v95
	v_div_scale_f32 v85, vcc, 1.0, v82, 1.0
	v_rcp_f32_e32 v102, v101
	v_mul_f32_e32 v86, v85, v84
	v_rcp_f32_e32 v108, v107
	v_fma_f32 v87, -v83, v86, v85
	v_fma_f32 v93, -v89, v90, 1.0
	v_fmac_f32_e32 v86, v87, v84
	v_fma_f32 v99, -v95, v96, 1.0
	v_fma_f32 v83, -v83, v86, v85
	v_fma_f32 v105, -v101, v102, 1.0
	v_div_fmas_f32 v83, v83, v84, v86
	v_fma_f32 v111, -v107, v108, 1.0
	v_fmac_f32_e32 v90, v93, v90
	v_fmac_f32_e32 v96, v99, v96
	v_fmac_f32_e32 v102, v105, v102
	v_fmac_f32_e32 v108, v111, v108
	v_div_fixup_f32 v65, v65, v64, 1.0
	v_div_fixup_f32 v71, v71, v70, 1.0
	v_div_fixup_f32 v77, v77, v76, 1.0
	v_div_fixup_f32 v83, v83, v82, 1.0
	v_mul_f32_e32 v65, v56, v65
	v_mul_f32_e32 v71, v57, v71
	v_mul_f32_e32 v77, v58, v77
	v_mul_f32_e32 v83, v59, v83
	v_mul_f32_e32 v65, v40, v65
	v_mul_f32_e32 v71, v41, v71
	v_mul_f32_e32 v77, v42, v77
	v_mul_f32_e32 v83, v43, v83
	v_cvt_pk_bf16_f32 v65, v65, v65
	v_cvt_pk_bf16_f32 v71, v71, v71
	v_cvt_pk_bf16_f32 v77, v77, v77
	v_cvt_pk_bf16_f32 v83, v83, v83
	ds_write_b16 v112, v65 offset:1024
	ds_write_b16 v112, v71 offset:1088
	ds_write_b16 v112, v77 offset:1152
	ds_write_b16 v112, v83 offset:1216
	v_div_scale_f32 v91, vcc, 1.0, v88, 1.0
	v_mul_f32_e32 v92, v91, v90
	v_fma_f32 v93, -v89, v92, v91
	v_fmac_f32_e32 v92, v93, v90
	v_fma_f32 v89, -v89, v92, v91
	v_div_fmas_f32 v89, v89, v90, v92
	v_div_scale_f32 v97, vcc, 1.0, v94, 1.0
	v_mul_f32_e32 v98, v97, v96
	v_fma_f32 v99, -v95, v98, v97
	v_fmac_f32_e32 v98, v99, v96
	v_fma_f32 v95, -v95, v98, v97
	v_div_fmas_f32 v95, v95, v96, v98
	v_div_scale_f32 v103, vcc, 1.0, v100, 1.0
	v_mul_f32_e32 v104, v103, v102
	v_fma_f32 v105, -v101, v104, v103
	v_fmac_f32_e32 v104, v105, v102
	v_fma_f32 v101, -v101, v104, v103
	v_div_fmas_f32 v101, v101, v102, v104
	v_div_scale_f32 v109, vcc, 1.0, v106, 1.0
	v_mul_f32_e32 v110, v109, v108
	v_fma_f32 v111, -v107, v110, v109
	v_fmac_f32_e32 v110, v111, v108
	v_fma_f32 v107, -v107, v110, v109
	v_div_fmas_f32 v107, v107, v108, v110
	v_div_fixup_f32 v89, v89, v88, 1.0
	v_div_fixup_f32 v95, v95, v94, 1.0
	v_div_fixup_f32 v101, v101, v100, 1.0
	v_div_fixup_f32 v107, v107, v106, 1.0
	v_mul_f32_e32 v89, v60, v89
	v_mul_f32_e32 v95, v61, v95
	v_mul_f32_e32 v101, v62, v101
	v_mul_f32_e32 v107, v63, v107
	v_mul_f32_e32 v89, v44, v89
	v_mul_f32_e32 v95, v45, v95
	v_mul_f32_e32 v101, v46, v101
	v_mul_f32_e32 v107, v47, v107
	v_cvt_pk_bf16_f32 v89, v89, v89
	v_cvt_pk_bf16_f32 v95, v95, v95
	v_cvt_pk_bf16_f32 v101, v101, v101
	v_cvt_pk_bf16_f32 v107, v107, v107
	ds_write_b16 v112, v89 offset:1536
	ds_write_b16 v112, v95 offset:1600
	ds_write_b16 v112, v101 offset:1664
	ds_write_b16 v112, v107 offset:1728
	ds_read_b128 v[120:123], v113
	ds_read_b128 v[124:127], v113 offset:1024
	s_waitcnt lgkmcnt(0)
	global_store_dwordx4 v114, v[120:123], s[98:99]
	s_add_u32 s98, s98, 0x16000
	s_addc_u32 s99, s99, 0
	global_store_dwordx4 v114, v[124:127], s[98:99]
	s_add_u32 s98, s98, 0x16000
	s_addc_u32 s99, s99, 0
	s_add_u32 s101, s101, 1
	s_cmp_lt_u32 s101, 2
	s_cbranch_scc0 .Lffl2_done
	v_mov_b32_e32 v48, v16
	v_mov_b32_e32 v49, v17
	v_mov_b32_e32 v50, v18
	v_mov_b32_e32 v51, v19
	v_mov_b32_e32 v52, v20
	v_mov_b32_e32 v53, v21
	v_mov_b32_e32 v54, v22
	v_mov_b32_e32 v55, v23
	v_mov_b32_e32 v56, v24
	v_mov_b32_e32 v57, v25
	v_mov_b32_e32 v58, v26
	v_mov_b32_e32 v59, v27
	v_mov_b32_e32 v60, v28
	v_mov_b32_e32 v61, v29
	v_mov_b32_e32 v62, v30
	v_mov_b32_e32 v63, v31
	v_mov_b32_e32 v32, v0
	v_mov_b32_e32 v33, v1
	v_mov_b32_e32 v34, v2
	v_mov_b32_e32 v35, v3
	v_mov_b32_e32 v36, v4
	v_mov_b32_e32 v37, v5
	v_mov_b32_e32 v38, v6
	v_mov_b32_e32 v39, v7
	v_mov_b32_e32 v40, v8
	v_mov_b32_e32 v41, v9
	v_mov_b32_e32 v42, v10
	v_mov_b32_e32 v43, v11
	v_mov_b32_e32 v44, v12
	v_mov_b32_e32 v45, v13
	v_mov_b32_e32 v46, v14
	v_mov_b32_e32 v47, v15
	s_branch .Lffl2_iter
.Lffl2_done:
	s_add_i32 s57, s57, s92
	s_cmpk_gt_i32 s57, 0x107f
	s_cbranch_scc1 .LBB0_1043

.Lffl6_iter:
	v_mul_f32_e32 v64, 0xbfb8aa3b, v48
	v_mul_f32_e32 v70, 0xbfb8aa3b, v49
	v_mul_f32_e32 v76, 0xbfb8aa3b, v50
	v_mul_f32_e32 v82, 0xbfb8aa3b, v51
	v_exp_f32_e32 v64, v64
	v_exp_f32_e32 v70, v70
	v_exp_f32_e32 v76, v76
	v_exp_f32_e32 v82, v82
	v_add_f32_e32 v64, 1.0, v64
	v_add_f32_e32 v70, 1.0, v70
	v_add_f32_e32 v76, 1.0, v76
	v_add_f32_e32 v82, 1.0, v82
	v_div_scale_f32 v65, s[4:5], v64, v64, 1.0
	v_div_scale_f32 v71, s[4:5], v70, v70, 1.0
	v_div_scale_f32 v77, s[4:5], v76, v76, 1.0
	v_div_scale_f32 v83, s[4:5], v82, v82, 1.0
	v_rcp_f32_e32 v66, v65
	v_rcp_f32_e32 v72, v71
	v_rcp_f32_e32 v78, v77
	v_rcp_f32_e32 v84, v83
	v_fma_f32 v69, -v65, v66, 1.0
	v_fma_f32 v75, -v71, v72, 1.0
	v_fma_f32 v81, -v77, v78, 1.0
	v_fma_f32 v87, -v83, v84, 1.0
	v_fmac_f32_e32 v66, v69, v66
	v_fmac_f32_e32 v72, v75, v72
	v_fmac_f32_e32 v78, v81, v78
	v_fmac_f32_e32 v84, v87, v84
	v_div_scale_f32 v67, vcc, 1.0, v64, 1.0
	v_mul_f32_e32 v88, 0xbfb8aa3b, v52
	v_mul_f32_e32 v68, v67, v66
	v_mul_f32_e32 v94, 0xbfb8aa3b, v53
	v_fma_f32 v69, -v65, v68, v67
	v_mul_f32_e32 v100, 0xbfb8aa3b, v54
	v_fmac_f32_e32 v68, v69, v66
	v_mul_f32_e32 v106, 0xbfb8aa3b, v55
	v_fma_f32 v65, -v65, v68, v67
	v_exp_f32_e32 v88, v88
	v_div_fmas_f32 v65, v65, v66, v68
	v_exp_f32_e32 v94, v94
	v_div_scale_f32 v73, vcc, 1.0, v70, 1.0
	v_exp_f32_e32 v100, v100
	v_mul_f32_e32 v74, v73, v72
	v_exp_f32_e32 v106, v106
	v_fma_f32 v75, -v71, v74, v73
	v_add_f32_e32 v88, 1.0, v88
	v_fmac_f32_e32 v74, v75, v72
	v_add_f32_e32 v94, 1.0, v94
	v_fma_f32 v71, -v71, v74, v73
	v_add_f32_e32 v100, 1.0, v100
	v_div_fmas_f32 v71, v71, v72, v74
	v_add_f32_e32 v106, 1.0, v106
	v_div_scale_f32 v79, vcc, 1.0, v76, 1.0
	v_div_scale_f32 v89, s[4:5], v88, v88, 1.0
	v_mul_f32_e32 v80, v79, v78
	v_div_scale_f32 v95, s[4:5], v94, v94, 1.0
	v_fma_f32 v81, -v77, v80, v79
	v_div_scale_f32 v101, s[4:5], v100, v100, 1.0
	v_fmac_f32_e32 v80, v81, v78
	v_div_scale_f32 v107, s[4:5], v106, v106, 1.0
	v_fma_f32 v77, -v77, v80, v79
	v_rcp_f32_e32 v90, v89
	v_div_fmas_f32 v77, v77, v78, v80
	v_rcp_f32_e32 v96, v95
	v_div_scale_f32 v85, vcc, 1.0, v82, 1.0
	v_rcp_f32_e32 v102, v101
	v_mul_f32_e32 v86, v85, v84
	v_rcp_f32_e32 v108, v107
	v_fma_f32 v87, -v83, v86, v85
	v_fma_f32 v93, -v89, v90, 1.0
	v_fmac_f32_e32 v86, v87, v84
	v_fma_f32 v99, -v95, v96, 1.0
	v_fma_f32 v83, -v83, v86, v85
	v_fma_f32 v105, -v101, v102, 1.0
	v_div_fmas_f32 v83, v83, v84, v86
	v_fma_f32 v111, -v107, v108, 1.0
	v_fmac_f32_e32 v90, v93, v90
	v_fmac_f32_e32 v96, v99, v96
	v_fmac_f32_e32 v102, v105, v102
	v_fmac_f32_e32 v108, v111, v108
	v_div_fixup_f32 v65, v65, v64, 1.0
	v_div_fixup_f32 v71, v71, v70, 1.0
	v_div_fixup_f32 v77, v77, v76, 1.0
	v_div_fixup_f32 v83, v83, v82, 1.0
	v_mul_f32_e32 v65, v48, v65
	v_mul_f32_e32 v71, v49, v71
	v_mul_f32_e32 v77, v50, v77
	v_mul_f32_e32 v83, v51, v83
	v_mul_f32_e32 v65, v32, v65
	v_mul_f32_e32 v71, v33, v71
	v_mul_f32_e32 v77, v34, v77
	v_mul_f32_e32 v83, v35, v83
	v_cvt_pk_bf16_f32 v65, v65, v65
	v_cvt_pk_bf16_f32 v71, v71, v71
	v_cvt_pk_bf16_f32 v77, v77, v77
	v_cvt_pk_bf16_f32 v83, v83, v83
	ds_write_b16 v112, v65
	ds_write_b16 v112, v71 offset:64
	ds_write_b16 v112, v77 offset:128
	ds_write_b16 v112, v83 offset:192
	v_div_scale_f32 v91, vcc, 1.0, v88, 1.0
	v_mul_f32_e32 v64, 0xbfb8aa3b, v56
	v_mul_f32_e32 v92, v91, v90
	v_mul_f32_e32 v70, 0xbfb8aa3b, v57
	v_fma_f32 v93, -v89, v92, v91
	v_mul_f32_e32 v76, 0xbfb8aa3b, v58
	v_fmac_f32_e32 v92, v93, v90
	v_mul_f32_e32 v82, 0xbfb8aa3b, v59
	v_fma_f32 v89, -v89, v92, v91
	v_exp_f32_e32 v64, v64
	v_div_fmas_f32 v89, v89, v90, v92
	v_exp_f32_e32 v70, v70
	v_div_scale_f32 v97, vcc, 1.0, v94, 1.0
	v_exp_f32_e32 v76, v76
	v_mul_f32_e32 v98, v97, v96
	v_exp_f32_e32 v82, v82
	v_fma_f32 v99, -v95, v98, v97
	v_add_f32_e32 v64, 1.0, v64
	v_fmac_f32_e32 v98, v99, v96
	v_add_f32_e32 v70, 1.0, v70
	v_fma_f32 v95, -v95, v98, v97
	v_add_f32_e32 v76, 1.0, v76
	v_div_fmas_f32 v95, v95, v96, v98
	v_add_f32_e32 v82, 1.0, v82
	v_div_scale_f32 v103, vcc, 1.0, v100, 1.0
	v_div_scale_f32 v65, s[4:5], v64, v64, 1.0
	v_mul_f32_e32 v104, v103, v102
	v_div_scale_f32 v71, s[4:5], v70, v70, 1.0
	v_fma_f32 v105, -v101, v104, v103
	v_div_scale_f32 v77, s[4:5], v76, v76, 1.0
	v_fmac_f32_e32 v104, v105, v102
	v_div_scale_f32 v83, s[4:5], v82, v82, 1.0
	v_fma_f32 v101, -v101, v104, v103
	v_rcp_f32_e32 v66, v65
	v_div_fmas_f32 v101, v101, v102, v104
	v_rcp_f32_e32 v72, v71
	v_div_scale_f32 v109, vcc, 1.0, v106, 1.0
	v_rcp_f32_e32 v78, v77
	v_mul_f32_e32 v110, v109, v108
	v_rcp_f32_e32 v84, v83
	v_fma_f32 v111, -v107, v110, v109
	v_fma_f32 v69, -v65, v66, 1.0
	v_fmac_f32_e32 v110, v111, v108
	v_fma_f32 v75, -v71, v72, 1.0
	v_fma_f32 v107, -v107, v110, v109
	v_fma_f32 v81, -v77, v78, 1.0
	v_div_fmas_f32 v107, v107, v108, v110
	v_fma_f32 v87, -v83, v84, 1.0
	v_fmac_f32_e32 v66, v69, v66
	v_fmac_f32_e32 v72, v75, v72
	v_fmac_f32_e32 v78, v81, v78
	v_fmac_f32_e32 v84, v87, v84
	v_div_fixup_f32 v89, v89, v88, 1.0
	v_div_fixup_f32 v95, v95, v94, 1.0
	v_div_fixup_f32 v101, v101, v100, 1.0
	v_div_fixup_f32 v107, v107, v106, 1.0
	v_mul_f32_e32 v89, v52, v89
	v_mul_f32_e32 v95, v53, v95
	v_mul_f32_e32 v101, v54, v101
	v_mul_f32_e32 v107, v55, v107
	v_mul_f32_e32 v89, v36, v89
	v_mul_f32_e32 v95, v37, v95
	v_mul_f32_e32 v101, v38, v101
	v_mul_f32_e32 v107, v39, v107
	v_cvt_pk_bf16_f32 v89, v89, v89
	v_cvt_pk_bf16_f32 v95, v95, v95
	v_cvt_pk_bf16_f32 v101, v101, v101
	v_cvt_pk_bf16_f32 v107, v107, v107
	ds_write_b16 v112, v89 offset:512
	ds_write_b16 v112, v95 offset:576
	ds_write_b16 v112, v101 offset:640
	ds_write_b16 v112, v107 offset:704
	v_div_scale_f32 v67, vcc, 1.0, v64, 1.0
	v_mul_f32_e32 v88, 0xbfb8aa3b, v60
	v_mul_f32_e32 v68, v67, v66
	v_mul_f32_e32 v94, 0xbfb8aa3b, v61
	v_fma_f32 v69, -v65, v68, v67
	v_mul_f32_e32 v100, 0xbfb8aa3b, v62
	v_fmac_f32_e32 v68, v69, v66
	v_mul_f32_e32 v106, 0xbfb8aa3b, v63
	v_fma_f32 v65, -v65, v68, v67
	v_exp_f32_e32 v88, v88
	v_div_fmas_f32 v65, v65, v66, v68
	v_exp_f32_e32 v94, v94
	v_div_scale_f32 v73, vcc, 1.0, v70, 1.0
	v_exp_f32_e32 v100, v100
	v_mul_f32_e32 v74, v73, v72
	v_exp_f32_e32 v106, v106
	v_fma_f32 v75, -v71, v74, v73
	v_add_f32_e32 v88, 1.0, v88
	v_fmac_f32_e32 v74, v75, v72
	v_add_f32_e32 v94, 1.0, v94
	v_fma_f32 v71, -v71, v74, v73
	v_add_f32_e32 v100, 1.0, v100
	v_div_fmas_f32 v71, v71, v72, v74
	v_add_f32_e32 v106, 1.0, v106
	v_div_scale_f32 v79, vcc, 1.0, v76, 1.0
	v_div_scale_f32 v89, s[4:5], v88, v88, 1.0
	v_mul_f32_e32 v80, v79, v78
	v_div_scale_f32 v95, s[4:5], v94, v94, 1.0
	v_fma_f32 v81, -v77, v80, v79
	v_div_scale_f32 v101, s[4:5], v100, v100, 1.0
	v_fmac_f32_e32 v80, v81, v78
	v_div_scale_f32 v107, s[4:5], v106, v106, 1.0
	v_fma_f32 v77, -v77, v80, v79
	v_rcp_f32_e32 v90, v89
	v_div_fmas_f32 v77, v77, v78, v80
	v_rcp_f32_e32 v96, v95
	v_div_scale_f32 v85, vcc, 1.0, v82, 1.0
	v_rcp_f32_e32 v102, v101
	v_mul_f32_e32 v86, v85, v84
	v_rcp_f32_e32 v108, v107
	v_fma_f32 v87, -v83, v86, v85
	v_fma_f32 v93, -v89, v90, 1.0
	v_fmac_f32_e32 v86, v87, v84
	v_fma_f32 v99, -v95, v96, 1.0
	v_fma_f32 v83, -v83, v86, v85
	v_fma_f32 v105, -v101, v102, 1.0
	v_div_fmas_f32 v83, v83, v84, v86
	v_fma_f32 v111, -v107, v108, 1.0
	v_fmac_f32_e32 v90, v93, v90
	v_fmac_f32_e32 v96, v99, v96
	v_fmac_f32_e32 v102, v105, v102
	v_fmac_f32_e32 v108, v111, v108
	v_div_fixup_f32 v65, v65, v64, 1.0
	v_div_fixup_f32 v71, v71, v70, 1.0
	v_div_fixup_f32 v77, v77, v76, 1.0
	v_div_fixup_f32 v83, v83, v82, 1.0
	v_mul_f32_e32 v65, v56, v65
	v_mul_f32_e32 v71, v57, v71
	v_mul_f32_e32 v77, v58, v77
	v_mul_f32_e32 v83, v59, v83
	v_mul_f32_e32 v65, v40, v65
	v_mul_f32_e32 v71, v41, v71
	v_mul_f32_e32 v77, v42, v77
	v_mul_f32_e32 v83, v43, v83
	v_cvt_pk_bf16_f32 v65, v65, v65
	v_cvt_pk_bf16_f32 v71, v71, v71
	v_cvt_pk_bf16_f32 v77, v77, v77
	v_cvt_pk_bf16_f32 v83, v83, v83
	ds_write_b16 v112, v65 offset:1024
	ds_write_b16 v112, v71 offset:1088
	ds_write_b16 v112, v77 offset:1152
	ds_write_b16 v112, v83 offset:1216
	v_div_scale_f32 v91, vcc, 1.0, v88, 1.0
	v_mul_f32_e32 v92, v91, v90
	v_fma_f32 v93, -v89, v92, v91
	v_fmac_f32_e32 v92, v93, v90
	v_fma_f32 v89, -v89, v92, v91
	v_div_fmas_f32 v89, v89, v90, v92
	v_div_scale_f32 v97, vcc, 1.0, v94, 1.0
	v_mul_f32_e32 v98, v97, v96
	v_fma_f32 v99, -v95, v98, v97
	v_fmac_f32_e32 v98, v99, v96
	v_fma_f32 v95, -v95, v98, v97
	v_div_fmas_f32 v95, v95, v96, v98
	v_div_scale_f32 v103, vcc, 1.0, v100, 1.0
	v_mul_f32_e32 v104, v103, v102
	v_fma_f32 v105, -v101, v104, v103
	v_fmac_f32_e32 v104, v105, v102
	v_fma_f32 v101, -v101, v104, v103
	v_div_fmas_f32 v101, v101, v102, v104
	v_div_scale_f32 v109, vcc, 1.0, v106, 1.0
	v_mul_f32_e32 v110, v109, v108
	v_fma_f32 v111, -v107, v110, v109
	v_fmac_f32_e32 v110, v111, v108
	v_fma_f32 v107, -v107, v110, v109
	v_div_fmas_f32 v107, v107, v108, v110
	v_div_fixup_f32 v89, v89, v88, 1.0
	v_div_fixup_f32 v95, v95, v94, 1.0
	v_div_fixup_f32 v101, v101, v100, 1.0
	v_div_fixup_f32 v107, v107, v106, 1.0
	v_mul_f32_e32 v89, v60, v89
	v_mul_f32_e32 v95, v61, v95
	v_mul_f32_e32 v101, v62, v101
	v_mul_f32_e32 v107, v63, v107
	v_mul_f32_e32 v89, v44, v89
	v_mul_f32_e32 v95, v45, v95
	v_mul_f32_e32 v101, v46, v101
	v_mul_f32_e32 v107, v47, v107
	v_cvt_pk_bf16_f32 v89, v89, v89
	v_cvt_pk_bf16_f32 v95, v95, v95
	v_cvt_pk_bf16_f32 v101, v101, v101
	v_cvt_pk_bf16_f32 v107, v107, v107
	ds_write_b16 v112, v89 offset:1536
	ds_write_b16 v112, v95 offset:1600
	ds_write_b16 v112, v101 offset:1664
	ds_write_b16 v112, v107 offset:1728
	ds_read_b128 v[120:123], v113
	ds_read_b128 v[124:127], v113 offset:1024
	s_waitcnt lgkmcnt(0)
	global_store_dwordx4 v114, v[120:123], s[98:99]
	s_add_u32 s98, s98, 0x16000
	s_addc_u32 s99, s99, 0
	global_store_dwordx4 v114, v[124:127], s[98:99]
	s_add_u32 s98, s98, 0x16000
	s_addc_u32 s99, s99, 0
	s_add_u32 s101, s101, 1
	s_cmp_lt_u32 s101, 2
	s_cbranch_scc0 .Lffl6_done
	v_mov_b32_e32 v48, v16
	v_mov_b32_e32 v49, v17
	v_mov_b32_e32 v50, v18
	v_mov_b32_e32 v51, v19
	v_mov_b32_e32 v52, v20
	v_mov_b32_e32 v53, v21
	v_mov_b32_e32 v54, v22
	v_mov_b32_e32 v55, v23
	v_mov_b32_e32 v56, v24
	v_mov_b32_e32 v57, v25
	v_mov_b32_e32 v58, v26
	v_mov_b32_e32 v59, v27
	v_mov_b32_e32 v60, v28
	v_mov_b32_e32 v61, v29
	v_mov_b32_e32 v62, v30
	v_mov_b32_e32 v63, v31
	v_mov_b32_e32 v32, v0
	v_mov_b32_e32 v33, v1
	v_mov_b32_e32 v34, v2
	v_mov_b32_e32 v35, v3
	v_mov_b32_e32 v36, v4
	v_mov_b32_e32 v37, v5
	v_mov_b32_e32 v38, v6
	v_mov_b32_e32 v39, v7
	v_mov_b32_e32 v40, v8
	v_mov_b32_e32 v41, v9
	v_mov_b32_e32 v42, v10
	v_mov_b32_e32 v43, v11
	v_mov_b32_e32 v44, v12
	v_mov_b32_e32 v45, v13
	v_mov_b32_e32 v46, v14
	v_mov_b32_e32 v47, v15
	s_branch .Lffl6_iter
.Lffl6_done:
	s_add_i32 s47, s47, s92
	s_cmpk_gt_i32 s47, 0x107f
	s_cbranch_scc1 .LBB0_2292
